# code placement: a second 4-byte pad at kernel entry (first phases shifted by 4 bytes, later ones by 8)
# baseline (speedup 1.0000x reference)
; #define LAS __attribute__((address_space(3)))
; __global__ void __launch_bounds__(512, 2) fwd_megakernel(Ptrs Parg) {
;     ...
;     volatile LAS unsigned* misc = (volatile LAS unsigned*)((LAS unsigned char*)lds + (LDS_BYTES - 16));
;     if (threadIdx.x < 4) misc[threadIdx.x] = 0u;
;     if ((threadIdx.x & 63) == 0) { const unsigned hw = (unsigned)__builtin_amdgcn_s_getreg((5 << 11) | 4) & 63u; ((volatile LAS unsigned*)((LAS unsigned char*)lds + pg8::WMAP_OFF))[hw] = threadIdx.x >> 6; }
_Z14fwd_megakernel4Ptrs:
	s_nop 0
	s_add_u32 s6, s0, 0xc0
	v_and_b32_e32 v1, 0x3ff, v0
	s_addc_u32 s7, s1, 0
	v_cmp_gt_u32_e32 vcc, 4, v1
	s_and_saveexec_b64 s[4:5], vcc
	v_lshl_add_u32 v2, v1, 2, 0
	v_add_u32_e32 v2, 0x27ff0, v2
	v_mov_b32_e32 v3, 0
	ds_write_b32 v2, v3
	s_or_b64 exec, exec, s[4:5]
	s_load_dwordx2 s[48:49], s[0:1], 0xb8
	v_and_b32_e32 v2, 63, v1
	v_cmp_eq_u32_e32 vcc, 0, v2
	s_and_saveexec_b64 s[4:5], vcc
	s_cbranch_execz .LBB0_4
	s_getreg_b32 s3, hwreg(HW_REG_HW_ID, 0, 6)
	s_and_b32 s3, s3, 63
	s_lshl_b32 s3, s3, 2
	s_add_i32 s3, s3, 0
	s_add_i32 s3, s3, 0x27ef0
	v_lshrrev_b32_e32 v2, 6, v1
	v_mov_b32_e32 v3, s3
	ds_write_b32 v3, v2
